# nt stores in the other GEMM epilogues as well (P1 fp8 gates, P3 merge, P4 out-projection)
# baseline (speedup 1.0000x reference)
.LBB0_134:
	s_lshl_b32 s88, s26, 8
	s_lshl_b32 s89, s48, 3
	s_add_i32 s88, s88, s89
	s_mul_i32 s88, s88, 0xc000
	s_add_u32 s86, s74, s88
	s_addc_u32 s87, s75, 0
	s_add_u32 s86, s86, 0x8000
	s_addc_u32 s87, s87, 0
	v_lshlrev_b32_e32 v240, 4, v183
	v_lshl_add_u32 v2, s48, 8, v186
	v_lshl_add_u32 v4, s26, 8, v184
	v_ashrrev_i32_e32 v3, 31, v2
	v_mov_b64_e32 v[0:1], s[74:75]
	v_mad_i64_i32 v[6:7], s[28:29], v4, s47, v[0:1]
	v_lshlrev_b64 v[2:3], 1, v[2:3]
	s_nop 15
	s_nop 15
	v_lshl_add_u64 v[10:11], v[6:7], 0, v[2:3]
	v_pk_mul_f32 v[6:7], v[158:159], s[14:15] op_sel_hi:[1,0]
	v_pk_mul_f32 v[8:9], v[156:157], s[14:15] op_sel_hi:[1,0]
	v_pk_mul_f32 v[12:13], v[152:153], s[14:15] op_sel_hi:[1,0]
	v_pk_mul_f32 v[14:15], v[154:155], s[14:15] op_sel_hi:[1,0]
	v_mul_f32_e32 v6, 0xbfb8aa3b, v6
	v_mul_f32_e32 v5, 0xbfb8aa3b, v8
	v_mul_f32_e32 v8, 0xbfb8aa3b, v12
	v_mul_f32_e32 v12, 0xbfb8aa3b, v13
	v_exp_f32_e32 v6, v6
	v_mul_f32_e32 v13, 0xbfb8aa3b, v14
	v_exp_f32_e32 v13, v13
	v_mul_f32_e32 v7, 0xbfb8aa3b, v7
	v_add_f32_e32 v6, 1.0, v6
	v_mul_f32_e32 v9, 0xbfb8aa3b, v9
	v_rcp_f32_e32 v14, v6
	v_add_f32_e32 v6, 1.0, v13
	v_exp_f32_e32 v7, v7
	v_mul_f32_e32 v13, 0xbfb8aa3b, v15
	v_exp_f32_e32 v5, v5
	v_exp_f32_e32 v8, v8
	v_exp_f32_e32 v9, v9
	v_exp_f32_e32 v12, v12
	v_exp_f32_e32 v13, v13
	v_rcp_f32_e32 v15, v6
	v_add_f32_e32 v6, 1.0, v7
	v_add_f32_e32 v5, 1.0, v5
	v_add_f32_e32 v8, 1.0, v8
	v_add_f32_e32 v9, 1.0, v9
	v_add_f32_e32 v12, 1.0, v12
	v_rcp_f32_e32 v7, v6
	v_add_f32_e32 v6, 1.0, v13
	v_rcp_f32_e32 v5, v5
	v_rcp_f32_e32 v8, v8
	v_rcp_f32_e32 v9, v9
	v_rcp_f32_e32 v12, v12
	v_rcp_f32_e32 v13, v6
	v_cvt_pk_bf16_f32 v7, v14, v7
	v_cvt_pk_bf16_f32 v6, v5, v9
	v_cvt_pk_bf16_f32 v8, v8, v12
	v_cvt_pk_bf16_f32 v9, v15, v13
	global_store_dwordx4 v240, v[6:9], s[86:87] nt
	v_pk_mul_f32 v[12:13], v[144:145], s[14:15] op_sel_hi:[1,0]
	v_pk_mul_f32 v[14:15], v[146:147], s[14:15] op_sel_hi:[1,0]
	v_pk_mul_f32 v[6:7], v[150:151], s[14:15] op_sel_hi:[1,0]
	v_pk_mul_f32 v[8:9], v[148:149], s[14:15] op_sel_hi:[1,0]
	v_mul_f32_e32 v6, 0xbfb8aa3b, v6
	v_mul_f32_e32 v5, 0xbfb8aa3b, v8
	v_mul_f32_e32 v8, 0xbfb8aa3b, v12
	v_mul_f32_e32 v12, 0xbfb8aa3b, v13
	v_exp_f32_e32 v6, v6
	v_mul_f32_e32 v13, 0xbfb8aa3b, v14
	v_exp_f32_e32 v13, v13
	v_mul_f32_e32 v7, 0xbfb8aa3b, v7
	v_add_f32_e32 v6, 1.0, v6
	v_mul_f32_e32 v9, 0xbfb8aa3b, v9
	v_rcp_f32_e32 v14, v6
	v_add_f32_e32 v6, 1.0, v13
	v_exp_f32_e32 v7, v7
	v_mul_f32_e32 v13, 0xbfb8aa3b, v15
	v_exp_f32_e32 v5, v5
	v_exp_f32_e32 v8, v8
	v_exp_f32_e32 v9, v9
	v_exp_f32_e32 v12, v12
	v_exp_f32_e32 v13, v13
	v_rcp_f32_e32 v15, v6
	v_add_f32_e32 v6, 1.0, v7
	v_add_f32_e32 v5, 1.0, v5
	v_add_f32_e32 v8, 1.0, v8
	v_add_f32_e32 v9, 1.0, v9
	v_add_f32_e32 v12, 1.0, v12
	v_rcp_f32_e32 v7, v6
	v_add_f32_e32 v6, 1.0, v13
	v_rcp_f32_e32 v5, v5
	v_rcp_f32_e32 v8, v8
	v_rcp_f32_e32 v9, v9
	v_rcp_f32_e32 v12, v12
	v_rcp_f32_e32 v13, v6
	v_cvt_pk_bf16_f32 v7, v14, v7
	v_cvt_pk_bf16_f32 v6, v5, v9
	v_cvt_pk_bf16_f32 v8, v8, v12
	v_cvt_pk_bf16_f32 v9, v15, v13
	v_or_b32_e32 v5, 16, v4
	v_add_u32_e32 v241, 0x2000, v240
	global_store_dwordx4 v241, v[6:9], s[86:87] nt
	v_pk_mul_f32 v[12:13], v[136:137], s[14:15] op_sel_hi:[1,0]
	v_pk_mul_f32 v[14:15], v[138:139], s[14:15] op_sel_hi:[1,0]
	v_mad_i64_i32 v[6:7], s[28:29], v5, s47, v[0:1]
	v_lshl_add_u64 v[10:11], v[6:7], 0, v[2:3]
	v_pk_mul_f32 v[6:7], v[142:143], s[14:15] op_sel_hi:[1,0]
	v_pk_mul_f32 v[8:9], v[140:141], s[14:15] op_sel_hi:[1,0]
	v_mul_f32_e32 v6, 0xbfb8aa3b, v6
	v_mul_f32_e32 v5, 0xbfb8aa3b, v8
	v_mul_f32_e32 v8, 0xbfb8aa3b, v12
	v_mul_f32_e32 v12, 0xbfb8aa3b, v13
	v_exp_f32_e32 v6, v6
	v_mul_f32_e32 v13, 0xbfb8aa3b, v14
	v_exp_f32_e32 v13, v13
	v_mul_f32_e32 v7, 0xbfb8aa3b, v7
	v_add_f32_e32 v6, 1.0, v6
	v_mul_f32_e32 v9, 0xbfb8aa3b, v9
	v_rcp_f32_e32 v14, v6
	v_add_f32_e32 v6, 1.0, v13
	v_exp_f32_e32 v7, v7
	v_mul_f32_e32 v13, 0xbfb8aa3b, v15
	v_exp_f32_e32 v5, v5
	v_exp_f32_e32 v8, v8
	v_exp_f32_e32 v9, v9
	v_exp_f32_e32 v12, v12
	v_exp_f32_e32 v13, v13
	v_rcp_f32_e32 v15, v6
	v_add_f32_e32 v6, 1.0, v7
	v_add_f32_e32 v5, 1.0, v5
	v_add_f32_e32 v8, 1.0, v8
	v_add_f32_e32 v9, 1.0, v9
	v_add_f32_e32 v12, 1.0, v12
	v_rcp_f32_e32 v7, v6
	v_add_f32_e32 v6, 1.0, v13
	v_rcp_f32_e32 v5, v5
	v_rcp_f32_e32 v8, v8
	v_rcp_f32_e32 v9, v9
	v_rcp_f32_e32 v12, v12
	v_rcp_f32_e32 v13, v6
	v_cvt_pk_bf16_f32 v7, v14, v7
	v_cvt_pk_bf16_f32 v6, v5, v9
	v_cvt_pk_bf16_f32 v8, v8, v12
	v_cvt_pk_bf16_f32 v9, v15, v13
	v_add_u32_e32 v241, 0xc000, v240
	global_store_dwordx4 v241, v[6:9], s[86:87] nt
	v_pk_mul_f32 v[12:13], v[128:129], s[14:15] op_sel_hi:[1,0]
	v_pk_mul_f32 v[14:15], v[130:131], s[14:15] op_sel_hi:[1,0]
	v_pk_mul_f32 v[6:7], v[134:135], s[14:15] op_sel_hi:[1,0]
	v_pk_mul_f32 v[8:9], v[132:133], s[14:15] op_sel_hi:[1,0]
	v_mul_f32_e32 v6, 0xbfb8aa3b, v6
	v_mul_f32_e32 v5, 0xbfb8aa3b, v8
	v_mul_f32_e32 v8, 0xbfb8aa3b, v12
	v_mul_f32_e32 v12, 0xbfb8aa3b, v13
	v_exp_f32_e32 v6, v6
	v_mul_f32_e32 v13, 0xbfb8aa3b, v14
	v_exp_f32_e32 v13, v13
	v_mul_f32_e32 v7, 0xbfb8aa3b, v7
	v_add_f32_e32 v6, 1.0, v6
	v_mul_f32_e32 v9, 0xbfb8aa3b, v9
	v_rcp_f32_e32 v14, v6
	v_add_f32_e32 v6, 1.0, v13
	v_exp_f32_e32 v7, v7
	v_mul_f32_e32 v13, 0xbfb8aa3b, v15
	v_exp_f32_e32 v5, v5
	v_exp_f32_e32 v8, v8
	v_exp_f32_e32 v9, v9
	v_exp_f32_e32 v12, v12
	v_exp_f32_e32 v13, v13
	v_rcp_f32_e32 v15, v6
	v_add_f32_e32 v6, 1.0, v7
	v_add_f32_e32 v5, 1.0, v5
	v_add_f32_e32 v8, 1.0, v8
	v_add_f32_e32 v9, 1.0, v9
	v_add_f32_e32 v12, 1.0, v12
	v_rcp_f32_e32 v7, v6
	v_add_f32_e32 v6, 1.0, v13
	v_rcp_f32_e32 v5, v5
	v_rcp_f32_e32 v8, v8
	v_rcp_f32_e32 v9, v9
	v_rcp_f32_e32 v12, v12
	v_rcp_f32_e32 v13, v6
	v_cvt_pk_bf16_f32 v7, v14, v7
	v_cvt_pk_bf16_f32 v6, v5, v9
	v_cvt_pk_bf16_f32 v8, v8, v12
	v_cvt_pk_bf16_f32 v9, v15, v13
	v_or_b32_e32 v5, 32, v4
	v_add_u32_e32 v241, 0xe000, v240
	global_store_dwordx4 v241, v[6:9], s[86:87] nt
	v_pk_mul_f32 v[12:13], v[120:121], s[14:15] op_sel_hi:[1,0]
	v_pk_mul_f32 v[14:15], v[122:123], s[14:15] op_sel_hi:[1,0]
	v_mad_i64_i32 v[6:7], s[28:29], v5, s47, v[0:1]
	v_lshl_add_u64 v[10:11], v[6:7], 0, v[2:3]
	v_pk_mul_f32 v[6:7], v[126:127], s[14:15] op_sel_hi:[1,0]
	v_pk_mul_f32 v[8:9], v[124:125], s[14:15] op_sel_hi:[1,0]
	v_mul_f32_e32 v6, 0xbfb8aa3b, v6
	v_mul_f32_e32 v5, 0xbfb8aa3b, v8
	v_mul_f32_e32 v8, 0xbfb8aa3b, v12
	v_mul_f32_e32 v12, 0xbfb8aa3b, v13
	v_exp_f32_e32 v6, v6
	v_mul_f32_e32 v13, 0xbfb8aa3b, v14
	v_exp_f32_e32 v13, v13
	v_mul_f32_e32 v7, 0xbfb8aa3b, v7
	v_add_f32_e32 v6, 1.0, v6
	v_mul_f32_e32 v9, 0xbfb8aa3b, v9
	v_rcp_f32_e32 v14, v6
	v_add_f32_e32 v6, 1.0, v13
	v_exp_f32_e32 v7, v7
	v_mul_f32_e32 v13, 0xbfb8aa3b, v15
	v_exp_f32_e32 v5, v5
	v_exp_f32_e32 v8, v8
	v_exp_f32_e32 v9, v9
	v_exp_f32_e32 v12, v12
	v_exp_f32_e32 v13, v13
	v_rcp_f32_e32 v15, v6
	v_add_f32_e32 v6, 1.0, v7
	v_add_f32_e32 v5, 1.0, v5
	v_add_f32_e32 v8, 1.0, v8
	v_add_f32_e32 v9, 1.0, v9
	v_add_f32_e32 v12, 1.0, v12
	v_rcp_f32_e32 v7, v6
	v_add_f32_e32 v6, 1.0, v13
	v_rcp_f32_e32 v5, v5
	v_rcp_f32_e32 v8, v8
	v_rcp_f32_e32 v9, v9
	v_rcp_f32_e32 v12, v12
	v_rcp_f32_e32 v13, v6
	v_cvt_pk_bf16_f32 v7, v14, v7
	v_cvt_pk_bf16_f32 v6, v5, v9
	v_cvt_pk_bf16_f32 v8, v8, v12
	v_cvt_pk_bf16_f32 v9, v15, v13
	v_add_u32_e32 v241, 0x18000, v240
	global_store_dwordx4 v241, v[6:9], s[86:87] nt
	v_pk_mul_f32 v[12:13], v[112:113], s[14:15] op_sel_hi:[1,0]
	v_pk_mul_f32 v[14:15], v[114:115], s[14:15] op_sel_hi:[1,0]
	v_pk_mul_f32 v[6:7], v[118:119], s[14:15] op_sel_hi:[1,0]
	v_pk_mul_f32 v[8:9], v[116:117], s[14:15] op_sel_hi:[1,0]
	v_mul_f32_e32 v6, 0xbfb8aa3b, v6
	v_mul_f32_e32 v5, 0xbfb8aa3b, v8
	v_mul_f32_e32 v8, 0xbfb8aa3b, v12
	v_mul_f32_e32 v12, 0xbfb8aa3b, v13
	v_exp_f32_e32 v6, v6
	v_mul_f32_e32 v13, 0xbfb8aa3b, v14
	v_exp_f32_e32 v13, v13
	v_mul_f32_e32 v7, 0xbfb8aa3b, v7
	v_add_f32_e32 v6, 1.0, v6
	v_mul_f32_e32 v9, 0xbfb8aa3b, v9
	v_rcp_f32_e32 v14, v6
	v_add_f32_e32 v6, 1.0, v13
	v_exp_f32_e32 v7, v7
	v_mul_f32_e32 v13, 0xbfb8aa3b, v15
	v_exp_f32_e32 v5, v5
	v_exp_f32_e32 v8, v8
	v_exp_f32_e32 v9, v9
	v_exp_f32_e32 v12, v12
	v_exp_f32_e32 v13, v13
	v_rcp_f32_e32 v15, v6
	v_add_f32_e32 v6, 1.0, v7
	v_add_f32_e32 v5, 1.0, v5
	v_add_f32_e32 v8, 1.0, v8
	v_add_f32_e32 v9, 1.0, v9
	v_add_f32_e32 v12, 1.0, v12
	v_rcp_f32_e32 v7, v6
	v_add_f32_e32 v6, 1.0, v13
	v_rcp_f32_e32 v5, v5
	v_rcp_f32_e32 v8, v8
	v_rcp_f32_e32 v9, v9
	v_rcp_f32_e32 v12, v12
	v_rcp_f32_e32 v13, v6
	v_cvt_pk_bf16_f32 v7, v14, v7
	v_cvt_pk_bf16_f32 v6, v5, v9
	v_cvt_pk_bf16_f32 v8, v8, v12
	v_cvt_pk_bf16_f32 v9, v15, v13
	v_or_b32_e32 v5, 48, v4
	v_add_u32_e32 v241, 0x1a000, v240
	global_store_dwordx4 v241, v[6:9], s[86:87] nt
	v_pk_mul_f32 v[12:13], v[104:105], s[14:15] op_sel_hi:[1,0]
	v_pk_mul_f32 v[14:15], v[106:107], s[14:15] op_sel_hi:[1,0]
	v_mad_i64_i32 v[6:7], s[28:29], v5, s47, v[0:1]
	v_lshl_add_u64 v[10:11], v[6:7], 0, v[2:3]
	v_pk_mul_f32 v[6:7], v[110:111], s[14:15] op_sel_hi:[1,0]
	v_pk_mul_f32 v[8:9], v[108:109], s[14:15] op_sel_hi:[1,0]
	v_mul_f32_e32 v6, 0xbfb8aa3b, v6
	v_mul_f32_e32 v5, 0xbfb8aa3b, v8
	v_mul_f32_e32 v8, 0xbfb8aa3b, v12
	v_mul_f32_e32 v12, 0xbfb8aa3b, v13
	v_exp_f32_e32 v6, v6
	v_mul_f32_e32 v13, 0xbfb8aa3b, v14
	v_exp_f32_e32 v13, v13
	v_mul_f32_e32 v7, 0xbfb8aa3b, v7
	v_add_f32_e32 v6, 1.0, v6
	v_mul_f32_e32 v9, 0xbfb8aa3b, v9
	v_rcp_f32_e32 v14, v6
	v_add_f32_e32 v6, 1.0, v13
	v_exp_f32_e32 v7, v7
	v_mul_f32_e32 v13, 0xbfb8aa3b, v15
	v_exp_f32_e32 v5, v5
	v_exp_f32_e32 v8, v8
	v_exp_f32_e32 v9, v9
	v_exp_f32_e32 v12, v12
	v_exp_f32_e32 v13, v13
	v_rcp_f32_e32 v15, v6
	v_add_f32_e32 v6, 1.0, v7
	v_add_f32_e32 v5, 1.0, v5
	v_add_f32_e32 v8, 1.0, v8
	v_add_f32_e32 v9, 1.0, v9
	v_add_f32_e32 v12, 1.0, v12
	v_rcp_f32_e32 v7, v6
	v_add_f32_e32 v6, 1.0, v13
	v_rcp_f32_e32 v5, v5
	v_rcp_f32_e32 v8, v8
	v_rcp_f32_e32 v9, v9
	v_rcp_f32_e32 v12, v12
	v_rcp_f32_e32 v13, v6
	v_cvt_pk_bf16_f32 v7, v14, v7
	v_cvt_pk_bf16_f32 v6, v5, v9
	v_cvt_pk_bf16_f32 v8, v8, v12
	v_cvt_pk_bf16_f32 v9, v15, v13
	v_add_u32_e32 v241, 0x24000, v240
	global_store_dwordx4 v241, v[6:9], s[86:87] nt
	v_pk_mul_f32 v[12:13], v[96:97], s[14:15] op_sel_hi:[1,0]
	v_pk_mul_f32 v[14:15], v[98:99], s[14:15] op_sel_hi:[1,0]
	v_pk_mul_f32 v[6:7], v[102:103], s[14:15] op_sel_hi:[1,0]
	v_pk_mul_f32 v[8:9], v[100:101], s[14:15] op_sel_hi:[1,0]
	v_mul_f32_e32 v6, 0xbfb8aa3b, v6
	v_mul_f32_e32 v5, 0xbfb8aa3b, v8
	v_mul_f32_e32 v8, 0xbfb8aa3b, v12
	v_mul_f32_e32 v12, 0xbfb8aa3b, v13
	v_exp_f32_e32 v6, v6
	v_mul_f32_e32 v13, 0xbfb8aa3b, v14
	v_exp_f32_e32 v13, v13
	v_mul_f32_e32 v7, 0xbfb8aa3b, v7
	v_add_f32_e32 v6, 1.0, v6
	v_mul_f32_e32 v9, 0xbfb8aa3b, v9
	v_rcp_f32_e32 v14, v6
	v_add_f32_e32 v6, 1.0, v13
	v_exp_f32_e32 v7, v7
	v_mul_f32_e32 v13, 0xbfb8aa3b, v15
	v_exp_f32_e32 v5, v5
	v_exp_f32_e32 v8, v8
	v_exp_f32_e32 v9, v9
	v_exp_f32_e32 v12, v12
	v_exp_f32_e32 v13, v13
	v_rcp_f32_e32 v15, v6
	v_add_f32_e32 v6, 1.0, v7
	v_add_f32_e32 v5, 1.0, v5
	v_add_f32_e32 v8, 1.0, v8
	v_add_f32_e32 v9, 1.0, v9
	v_add_f32_e32 v12, 1.0, v12
	v_rcp_f32_e32 v7, v6
	v_add_f32_e32 v6, 1.0, v13
	v_rcp_f32_e32 v5, v5
	v_rcp_f32_e32 v8, v8
	v_rcp_f32_e32 v9, v9
	v_rcp_f32_e32 v12, v12
	v_rcp_f32_e32 v13, v6
	v_cvt_pk_bf16_f32 v7, v14, v7
	v_cvt_pk_bf16_f32 v6, v5, v9
	v_cvt_pk_bf16_f32 v8, v8, v12
	v_cvt_pk_bf16_f32 v9, v15, v13
	v_add_u32_e32 v5, 0x80, v4
	v_add_u32_e32 v241, 0x26000, v240
	global_store_dwordx4 v241, v[6:9], s[86:87] nt
	v_pk_mul_f32 v[12:13], v[88:89], s[14:15] op_sel_hi:[1,0]
	v_pk_mul_f32 v[14:15], v[90:91], s[14:15] op_sel_hi:[1,0]
	v_mad_i64_i32 v[6:7], s[28:29], v5, s47, v[0:1]
	v_lshl_add_u64 v[10:11], v[6:7], 0, v[2:3]
	v_pk_mul_f32 v[6:7], v[94:95], s[14:15] op_sel_hi:[1,0]
	v_pk_mul_f32 v[8:9], v[92:93], s[14:15] op_sel_hi:[1,0]
	v_mul_f32_e32 v6, 0xbfb8aa3b, v6
	v_mul_f32_e32 v5, 0xbfb8aa3b, v8
	v_mul_f32_e32 v8, 0xbfb8aa3b, v12
	v_mul_f32_e32 v12, 0xbfb8aa3b, v13
	v_exp_f32_e32 v6, v6
	v_mul_f32_e32 v13, 0xbfb8aa3b, v14
	v_exp_f32_e32 v13, v13
	v_mul_f32_e32 v7, 0xbfb8aa3b, v7
	v_add_f32_e32 v6, 1.0, v6
	v_mul_f32_e32 v9, 0xbfb8aa3b, v9
	v_rcp_f32_e32 v14, v6
	v_add_f32_e32 v6, 1.0, v13
	v_exp_f32_e32 v7, v7
	v_mul_f32_e32 v13, 0xbfb8aa3b, v15
	v_exp_f32_e32 v5, v5
	v_exp_f32_e32 v8, v8
	v_exp_f32_e32 v9, v9
	v_exp_f32_e32 v12, v12
	v_exp_f32_e32 v13, v13
	v_rcp_f32_e32 v15, v6
	v_add_f32_e32 v6, 1.0, v7
	v_add_f32_e32 v5, 1.0, v5
	v_add_f32_e32 v8, 1.0, v8
	v_add_f32_e32 v9, 1.0, v9
	v_add_f32_e32 v12, 1.0, v12
	v_rcp_f32_e32 v7, v6
	v_add_f32_e32 v6, 1.0, v13
	v_rcp_f32_e32 v5, v5
	v_rcp_f32_e32 v8, v8
	v_rcp_f32_e32 v9, v9
	v_rcp_f32_e32 v12, v12
	v_rcp_f32_e32 v13, v6
	v_cvt_pk_bf16_f32 v7, v14, v7
	v_cvt_pk_bf16_f32 v6, v5, v9
	v_cvt_pk_bf16_f32 v8, v8, v12
	v_cvt_pk_bf16_f32 v9, v15, v13
	v_add_u32_e32 v241, 0x30000, v240
	global_store_dwordx4 v241, v[6:9], s[86:87] nt
	v_pk_mul_f32 v[12:13], v[80:81], s[14:15] op_sel_hi:[1,0]
	v_pk_mul_f32 v[14:15], v[82:83], s[14:15] op_sel_hi:[1,0]
	v_pk_mul_f32 v[6:7], v[86:87], s[14:15] op_sel_hi:[1,0]
	v_pk_mul_f32 v[8:9], v[84:85], s[14:15] op_sel_hi:[1,0]
	v_mul_f32_e32 v6, 0xbfb8aa3b, v6
	v_mul_f32_e32 v5, 0xbfb8aa3b, v8
	v_mul_f32_e32 v8, 0xbfb8aa3b, v12
	v_mul_f32_e32 v12, 0xbfb8aa3b, v13
	v_exp_f32_e32 v6, v6
	v_mul_f32_e32 v13, 0xbfb8aa3b, v14
	v_exp_f32_e32 v13, v13
	v_mul_f32_e32 v7, 0xbfb8aa3b, v7
	v_add_f32_e32 v6, 1.0, v6
	v_mul_f32_e32 v9, 0xbfb8aa3b, v9
	v_rcp_f32_e32 v14, v6
	v_add_f32_e32 v6, 1.0, v13
	v_exp_f32_e32 v7, v7
	v_mul_f32_e32 v13, 0xbfb8aa3b, v15
	v_exp_f32_e32 v5, v5
	v_exp_f32_e32 v8, v8
	v_exp_f32_e32 v9, v9
	v_exp_f32_e32 v12, v12
	v_exp_f32_e32 v13, v13
	v_rcp_f32_e32 v15, v6
	v_add_f32_e32 v6, 1.0, v7
	v_add_f32_e32 v5, 1.0, v5
	v_add_f32_e32 v8, 1.0, v8
	v_add_f32_e32 v9, 1.0, v9
	v_add_f32_e32 v12, 1.0, v12
	v_rcp_f32_e32 v7, v6
	v_add_f32_e32 v6, 1.0, v13
	v_rcp_f32_e32 v5, v5
	v_rcp_f32_e32 v8, v8
	v_rcp_f32_e32 v9, v9
	v_rcp_f32_e32 v12, v12
	v_rcp_f32_e32 v13, v6
	v_cvt_pk_bf16_f32 v7, v14, v7
	v_cvt_pk_bf16_f32 v6, v5, v9
	v_cvt_pk_bf16_f32 v8, v8, v12
	v_cvt_pk_bf16_f32 v9, v15, v13
	v_add_u32_e32 v5, 0x90, v4
	v_add_u32_e32 v241, 0x32000, v240
	global_store_dwordx4 v241, v[6:9], s[86:87] nt
	v_pk_mul_f32 v[12:13], v[72:73], s[14:15] op_sel_hi:[1,0]
	v_pk_mul_f32 v[14:15], v[74:75], s[14:15] op_sel_hi:[1,0]
	v_mad_i64_i32 v[6:7], s[28:29], v5, s47, v[0:1]
	v_lshl_add_u64 v[10:11], v[6:7], 0, v[2:3]
	v_pk_mul_f32 v[6:7], v[78:79], s[14:15] op_sel_hi:[1,0]
	v_pk_mul_f32 v[8:9], v[76:77], s[14:15] op_sel_hi:[1,0]
	v_mul_f32_e32 v6, 0xbfb8aa3b, v6
	v_mul_f32_e32 v5, 0xbfb8aa3b, v8
	v_mul_f32_e32 v8, 0xbfb8aa3b, v12
	v_mul_f32_e32 v12, 0xbfb8aa3b, v13
	v_exp_f32_e32 v6, v6
	v_mul_f32_e32 v13, 0xbfb8aa3b, v14
	v_exp_f32_e32 v13, v13
	v_mul_f32_e32 v7, 0xbfb8aa3b, v7
	v_add_f32_e32 v6, 1.0, v6
	v_mul_f32_e32 v9, 0xbfb8aa3b, v9
	v_rcp_f32_e32 v14, v6
	v_add_f32_e32 v6, 1.0, v13
	v_exp_f32_e32 v7, v7
	v_mul_f32_e32 v13, 0xbfb8aa3b, v15
	v_exp_f32_e32 v5, v5
	v_exp_f32_e32 v8, v8
	v_exp_f32_e32 v9, v9
	v_exp_f32_e32 v12, v12
	v_exp_f32_e32 v13, v13
	v_rcp_f32_e32 v15, v6
	v_add_f32_e32 v6, 1.0, v7
	v_add_f32_e32 v5, 1.0, v5
	v_add_f32_e32 v8, 1.0, v8
	v_add_f32_e32 v9, 1.0, v9
	v_add_f32_e32 v12, 1.0, v12
	v_rcp_f32_e32 v7, v6
	v_add_f32_e32 v6, 1.0, v13
	v_rcp_f32_e32 v5, v5
	v_rcp_f32_e32 v8, v8
	v_rcp_f32_e32 v9, v9
	v_rcp_f32_e32 v12, v12
	v_rcp_f32_e32 v13, v6
	v_cvt_pk_bf16_f32 v7, v14, v7
	v_cvt_pk_bf16_f32 v6, v5, v9
	v_cvt_pk_bf16_f32 v8, v8, v12
	v_cvt_pk_bf16_f32 v9, v15, v13
	v_add_u32_e32 v241, 0x3c000, v240
	global_store_dwordx4 v241, v[6:9], s[86:87] nt
	v_pk_mul_f32 v[12:13], v[64:65], s[14:15] op_sel_hi:[1,0]
	v_pk_mul_f32 v[14:15], v[66:67], s[14:15] op_sel_hi:[1,0]
	v_pk_mul_f32 v[6:7], v[70:71], s[14:15] op_sel_hi:[1,0]
	v_pk_mul_f32 v[8:9], v[68:69], s[14:15] op_sel_hi:[1,0]
	v_mul_f32_e32 v6, 0xbfb8aa3b, v6
	v_mul_f32_e32 v5, 0xbfb8aa3b, v8
	v_mul_f32_e32 v8, 0xbfb8aa3b, v12
	v_mul_f32_e32 v12, 0xbfb8aa3b, v13
	v_exp_f32_e32 v6, v6
	v_mul_f32_e32 v13, 0xbfb8aa3b, v14
	v_exp_f32_e32 v13, v13
	v_mul_f32_e32 v7, 0xbfb8aa3b, v7
	v_add_f32_e32 v6, 1.0, v6
	v_mul_f32_e32 v9, 0xbfb8aa3b, v9
	v_rcp_f32_e32 v14, v6
	v_add_f32_e32 v6, 1.0, v13
	v_exp_f32_e32 v7, v7
	v_mul_f32_e32 v13, 0xbfb8aa3b, v15
	v_exp_f32_e32 v5, v5
	v_exp_f32_e32 v8, v8
	v_exp_f32_e32 v9, v9
	v_exp_f32_e32 v12, v12
	v_exp_f32_e32 v13, v13
	v_rcp_f32_e32 v15, v6
	v_add_f32_e32 v6, 1.0, v7
	v_add_f32_e32 v5, 1.0, v5
	v_add_f32_e32 v8, 1.0, v8
	v_add_f32_e32 v9, 1.0, v9
	v_add_f32_e32 v12, 1.0, v12
	v_rcp_f32_e32 v7, v6
	v_add_f32_e32 v6, 1.0, v13
	v_rcp_f32_e32 v5, v5
	v_rcp_f32_e32 v8, v8
	v_rcp_f32_e32 v9, v9
	v_rcp_f32_e32 v12, v12
	v_rcp_f32_e32 v13, v6
	v_cvt_pk_bf16_f32 v7, v14, v7
	v_cvt_pk_bf16_f32 v6, v5, v9
	v_cvt_pk_bf16_f32 v8, v8, v12
	v_cvt_pk_bf16_f32 v9, v15, v13
	v_add_u32_e32 v5, 0xa0, v4
	v_add_u32_e32 v241, 0x3e000, v240
	global_store_dwordx4 v241, v[6:9], s[86:87] nt
	v_pk_mul_f32 v[12:13], v[56:57], s[14:15] op_sel_hi:[1,0]
	v_pk_mul_f32 v[14:15], v[58:59], s[14:15] op_sel_hi:[1,0]
	v_mad_i64_i32 v[6:7], s[28:29], v5, s47, v[0:1]
	v_lshl_add_u64 v[10:11], v[6:7], 0, v[2:3]
	v_pk_mul_f32 v[6:7], v[62:63], s[14:15] op_sel_hi:[1,0]
	v_pk_mul_f32 v[8:9], v[60:61], s[14:15] op_sel_hi:[1,0]
	v_mul_f32_e32 v6, 0xbfb8aa3b, v6
	v_mul_f32_e32 v5, 0xbfb8aa3b, v8
	v_mul_f32_e32 v8, 0xbfb8aa3b, v12
	v_mul_f32_e32 v12, 0xbfb8aa3b, v13
	v_exp_f32_e32 v6, v6
	v_mul_f32_e32 v13, 0xbfb8aa3b, v14
	v_exp_f32_e32 v13, v13
	v_mul_f32_e32 v7, 0xbfb8aa3b, v7
	v_add_f32_e32 v6, 1.0, v6
	v_mul_f32_e32 v9, 0xbfb8aa3b, v9
	v_rcp_f32_e32 v14, v6
	v_add_f32_e32 v6, 1.0, v13
	v_exp_f32_e32 v7, v7
	v_mul_f32_e32 v13, 0xbfb8aa3b, v15
	v_exp_f32_e32 v5, v5
	v_exp_f32_e32 v8, v8
	v_exp_f32_e32 v9, v9
	v_exp_f32_e32 v12, v12
	v_exp_f32_e32 v13, v13
	v_rcp_f32_e32 v15, v6
	v_add_f32_e32 v6, 1.0, v7
	v_add_f32_e32 v5, 1.0, v5
	v_add_f32_e32 v8, 1.0, v8
	v_add_f32_e32 v9, 1.0, v9
	v_add_f32_e32 v12, 1.0, v12
	v_rcp_f32_e32 v7, v6
	v_add_f32_e32 v6, 1.0, v13
	v_rcp_f32_e32 v5, v5
	v_rcp_f32_e32 v8, v8
	v_rcp_f32_e32 v9, v9
	v_rcp_f32_e32 v12, v12
	v_rcp_f32_e32 v13, v6
	v_cvt_pk_bf16_f32 v7, v14, v7
	v_cvt_pk_bf16_f32 v6, v5, v9
	v_cvt_pk_bf16_f32 v8, v8, v12
	v_cvt_pk_bf16_f32 v9, v15, v13
	v_add_u32_e32 v241, 0x48000, v240
	global_store_dwordx4 v241, v[6:9], s[86:87] nt
	v_pk_mul_f32 v[12:13], v[48:49], s[14:15] op_sel_hi:[1,0]
	v_pk_mul_f32 v[14:15], v[50:51], s[14:15] op_sel_hi:[1,0]
	v_pk_mul_f32 v[6:7], v[54:55], s[14:15] op_sel_hi:[1,0]
	v_pk_mul_f32 v[8:9], v[52:53], s[14:15] op_sel_hi:[1,0]
	v_mul_f32_e32 v6, 0xbfb8aa3b, v6
	v_mul_f32_e32 v5, 0xbfb8aa3b, v8
	v_mul_f32_e32 v8, 0xbfb8aa3b, v12
	v_mul_f32_e32 v12, 0xbfb8aa3b, v13
	v_exp_f32_e32 v6, v6
	v_mul_f32_e32 v13, 0xbfb8aa3b, v14
	v_exp_f32_e32 v13, v13
	v_mul_f32_e32 v7, 0xbfb8aa3b, v7
	v_add_f32_e32 v6, 1.0, v6
	v_mul_f32_e32 v9, 0xbfb8aa3b, v9
	v_rcp_f32_e32 v14, v6
	v_add_f32_e32 v6, 1.0, v13
	v_exp_f32_e32 v7, v7
	v_mul_f32_e32 v13, 0xbfb8aa3b, v15
	v_exp_f32_e32 v5, v5
	v_exp_f32_e32 v8, v8
	v_exp_f32_e32 v9, v9
	v_exp_f32_e32 v12, v12
	v_exp_f32_e32 v13, v13
	v_rcp_f32_e32 v15, v6
	v_add_f32_e32 v6, 1.0, v7
	v_add_f32_e32 v5, 1.0, v5
	v_add_f32_e32 v8, 1.0, v8
	v_add_f32_e32 v9, 1.0, v9
	v_add_f32_e32 v12, 1.0, v12
	v_rcp_f32_e32 v7, v6
	v_add_f32_e32 v6, 1.0, v13
	v_rcp_f32_e32 v5, v5
	v_rcp_f32_e32 v8, v8
	v_rcp_f32_e32 v9, v9
	v_rcp_f32_e32 v12, v12
	v_rcp_f32_e32 v13, v6
	v_add_u32_e32 v4, 0xb0, v4
	v_mad_i64_i32 v[0:1], s[28:29], v4, s47, v[0:1]
	v_cvt_pk_bf16_f32 v6, v5, v9
	v_cvt_pk_bf16_f32 v7, v14, v7
	v_cvt_pk_bf16_f32 v8, v8, v12
	v_cvt_pk_bf16_f32 v9, v15, v13
	v_lshl_add_u64 v[4:5], v[0:1], 0, v[2:3]
	v_pk_mul_f32 v[0:1], v[46:47], s[14:15] op_sel_hi:[1,0]
	v_add_u32_e32 v241, 0x4a000, v240
	global_store_dwordx4 v241, v[6:9], s[86:87] nt
	v_mul_f32_e32 v0, 0xbfb8aa3b, v0
	v_exp_f32_e32 v0, v0
	v_pk_mul_f32 v[8:9], v[42:43], s[14:15] op_sel_hi:[1,0]
	v_pk_mul_f32 v[2:3], v[44:45], s[14:15] op_sel_hi:[1,0]
	v_mul_f32_e32 v8, 0xbfb8aa3b, v8
	v_exp_f32_e32 v8, v8
	v_pk_mul_f32 v[6:7], v[40:41], s[14:15] op_sel_hi:[1,0]
	v_add_f32_e32 v0, 1.0, v0
	v_mul_f32_e32 v1, 0xbfb8aa3b, v1
	v_mul_f32_e32 v2, 0xbfb8aa3b, v2
	v_mul_f32_e32 v6, 0xbfb8aa3b, v6
	v_mul_f32_e32 v3, 0xbfb8aa3b, v3
	v_mul_f32_e32 v7, 0xbfb8aa3b, v7
	v_rcp_f32_e32 v10, v0
	v_add_f32_e32 v0, 1.0, v8
	v_exp_f32_e32 v1, v1
	v_mul_f32_e32 v8, 0xbfb8aa3b, v9
	v_exp_f32_e32 v2, v2
	v_exp_f32_e32 v6, v6
	v_exp_f32_e32 v3, v3
	v_exp_f32_e32 v7, v7
	v_exp_f32_e32 v8, v8
	v_rcp_f32_e32 v9, v0
	v_add_f32_e32 v0, 1.0, v1
	v_add_f32_e32 v2, 1.0, v2
	v_add_f32_e32 v6, 1.0, v6
	v_add_f32_e32 v3, 1.0, v3
	v_add_f32_e32 v7, 1.0, v7
	v_rcp_f32_e32 v1, v0
	v_add_f32_e32 v0, 1.0, v8
	v_rcp_f32_e32 v2, v2
	v_rcp_f32_e32 v6, v6
	v_rcp_f32_e32 v3, v3
	v_rcp_f32_e32 v7, v7
	v_rcp_f32_e32 v8, v0
	v_cvt_pk_bf16_f32 v1, v10, v1
	v_cvt_pk_bf16_f32 v0, v2, v3
	v_cvt_pk_bf16_f32 v2, v6, v7
	v_cvt_pk_bf16_f32 v3, v9, v8
	v_add_u32_e32 v241, 0x54000, v240
	global_store_dwordx4 v241, v[0:3], s[86:87] nt
	v_pk_mul_f32 v[8:9], v[34:35], s[14:15] op_sel_hi:[1,0]
	v_pk_mul_f32 v[6:7], v[32:33], s[14:15] op_sel_hi:[1,0]
	v_pk_mul_f32 v[0:1], v[38:39], s[14:15] op_sel_hi:[1,0]
	v_mul_f32_e32 v8, 0xbfb8aa3b, v8
	v_mul_f32_e32 v0, 0xbfb8aa3b, v0
	v_exp_f32_e32 v0, v0
	v_exp_f32_e32 v8, v8
	v_pk_mul_f32 v[2:3], v[36:37], s[14:15] op_sel_hi:[1,0]
	v_mul_f32_e32 v1, 0xbfb8aa3b, v1
	v_add_f32_e32 v0, 1.0, v0
	v_mul_f32_e32 v2, 0xbfb8aa3b, v2
	v_mul_f32_e32 v6, 0xbfb8aa3b, v6
	v_mul_f32_e32 v3, 0xbfb8aa3b, v3
	v_mul_f32_e32 v7, 0xbfb8aa3b, v7
	v_rcp_f32_e32 v10, v0
	v_add_f32_e32 v0, 1.0, v8
	v_exp_f32_e32 v1, v1
	v_mul_f32_e32 v8, 0xbfb8aa3b, v9
	v_exp_f32_e32 v2, v2
	v_exp_f32_e32 v6, v6
	v_exp_f32_e32 v3, v3
	v_exp_f32_e32 v7, v7
	v_exp_f32_e32 v8, v8
	v_rcp_f32_e32 v9, v0
	v_add_f32_e32 v0, 1.0, v1
	v_add_f32_e32 v2, 1.0, v2
	v_add_f32_e32 v6, 1.0, v6
	v_add_f32_e32 v3, 1.0, v3
	v_add_f32_e32 v7, 1.0, v7
	v_rcp_f32_e32 v1, v0
	v_add_f32_e32 v0, 1.0, v8
	v_rcp_f32_e32 v2, v2
	v_rcp_f32_e32 v6, v6
	v_rcp_f32_e32 v3, v3
	v_rcp_f32_e32 v7, v7
	v_rcp_f32_e32 v8, v0
	v_cvt_pk_bf16_f32 v1, v10, v1
	v_cvt_pk_bf16_f32 v0, v2, v3
	v_cvt_pk_bf16_f32 v2, v6, v7
	v_cvt_pk_bf16_f32 v3, v9, v8
	s_andn2_b64 vcc, exec, s[20:21]
	s_mov_b64 s[20:21], -1
	v_add_u32_e32 v241, 0x56000, v240
	global_store_dwordx4 v241, v[0:3], s[86:87] nt
	s_cbranch_vccnz .LBB0_122
	s_andn2_b64 vcc, exec, s[8:9]
	s_cbranch_vccnz .LBB0_121
	s_barrier
	s_branch .LBB0_121

.Lp3e_half1:
	global_load_dwordx4 v[166:169], v142, s[76:77]
	global_load_dwordx4 v[170:173], v142, s[88:89]
	v_add_u32_e32 v145, 0xc000, v142
	global_load_dwordx4 v[174:177], v145, s[76:77]
	global_load_dwordx4 v[178:181], v145, s[88:89]
	v_add_u32_e32 v144, 0x18000, v142
	global_load_dwordx4 v[184:187], v144, s[76:77]
	global_load_dwordx4 v[188:191], v144, s[88:89]
	v_add_u32_e32 v145, 0x24000, v142
	global_load_dwordx4 v[192:195], v145, s[76:77]
	global_load_dwordx4 v[196:199], v145, s[88:89]
	v_add_u32_e32 v144, 0x30000, v142
	global_load_dwordx4 v[200:203], v144, s[76:77]
	global_load_dwordx4 v[204:207], v144, s[88:89]
	v_add_u32_e32 v145, 0x3c000, v142
	global_load_dwordx4 v[208:211], v145, s[76:77]
	global_load_dwordx4 v[212:215], v145, s[88:89]
	v_add_u32_e32 v144, 0x48000, v142
	global_load_dwordx4 v[216:219], v144, s[76:77]
	global_load_dwordx4 v[220:223], v144, s[88:89]
	v_add_u32_e32 v145, 0x54000, v142
	global_load_dwordx4 v[224:227], v145, s[76:77]
	global_load_dwordx4 v[228:231], v145, s[88:89]
	s_waitcnt vmcnt(15)
	v_lshlrev_b32_e32 v146, 16, v166
	v_and_b32_e32 v147, 0xffff0000, v166
	v_lshlrev_b32_e32 v148, 16, v167
	v_and_b32_e32 v149, 0xffff0000, v167
	v_lshlrev_b32_e32 v150, 16, v168
	v_and_b32_e32 v151, 0xffff0000, v168
	v_lshlrev_b32_e32 v152, 16, v169
	v_and_b32_e32 v153, 0xffff0000, v169
	v_pk_mul_f32 v[154:155], v[124:125], v[146:147]
	v_pk_mul_f32 v[156:157], v[126:127], v[148:149]
	v_pk_mul_f32 v[158:159], v[120:121], v[150:151]
	v_pk_mul_f32 v[160:161], v[122:123], v[152:153]
	v_cvt_pk_bf16_f32 v166, v154, v155
	v_cvt_pk_bf16_f32 v167, v156, v157
	v_cvt_pk_bf16_f32 v168, v158, v159
	v_cvt_pk_bf16_f32 v169, v160, v161
	global_store_dwordx4 v143, v[166:169], s[72:73] nt
	s_waitcnt vmcnt(15)
	v_lshlrev_b32_e32 v146, 16, v170
	v_and_b32_e32 v147, 0xffff0000, v170
	v_lshlrev_b32_e32 v148, 16, v171
	v_and_b32_e32 v149, 0xffff0000, v171
	v_lshlrev_b32_e32 v150, 16, v172
	v_and_b32_e32 v151, 0xffff0000, v172
	v_lshlrev_b32_e32 v152, 16, v173
	v_and_b32_e32 v153, 0xffff0000, v173
	v_pk_mul_f32 v[154:155], v[92:93], v[146:147]
	v_pk_mul_f32 v[156:157], v[94:95], v[148:149]
	v_pk_mul_f32 v[158:159], v[88:89], v[150:151]
	v_pk_mul_f32 v[160:161], v[90:91], v[152:153]
	v_cvt_pk_bf16_f32 v170, v154, v155
	v_cvt_pk_bf16_f32 v171, v156, v157
	v_cvt_pk_bf16_f32 v172, v158, v159
	v_cvt_pk_bf16_f32 v173, v160, v161
	global_store_dwordx4 v143, v[170:173], s[72:73] offset:256 nt
	s_waitcnt vmcnt(15)
	v_lshlrev_b32_e32 v146, 16, v174
	v_and_b32_e32 v147, 0xffff0000, v174
	v_lshlrev_b32_e32 v148, 16, v175
	v_and_b32_e32 v149, 0xffff0000, v175
	v_lshlrev_b32_e32 v150, 16, v176
	v_and_b32_e32 v151, 0xffff0000, v176
	v_lshlrev_b32_e32 v152, 16, v177
	v_and_b32_e32 v153, 0xffff0000, v177
	v_pk_mul_f32 v[154:155], v[116:117], v[146:147]
	v_pk_mul_f32 v[156:157], v[118:119], v[148:149]
	v_pk_mul_f32 v[158:159], v[112:113], v[150:151]
	v_pk_mul_f32 v[160:161], v[114:115], v[152:153]
	v_add_u32_e32 v145, 0x20000, v143
	v_cvt_pk_bf16_f32 v174, v154, v155
	v_cvt_pk_bf16_f32 v175, v156, v157
	v_cvt_pk_bf16_f32 v176, v158, v159
	v_cvt_pk_bf16_f32 v177, v160, v161
	global_store_dwordx4 v145, v[174:177], s[72:73] nt
	s_waitcnt vmcnt(15)
	v_lshlrev_b32_e32 v146, 16, v178
	v_and_b32_e32 v147, 0xffff0000, v178
	v_lshlrev_b32_e32 v148, 16, v179
	v_and_b32_e32 v149, 0xffff0000, v179
	v_lshlrev_b32_e32 v150, 16, v180
	v_and_b32_e32 v151, 0xffff0000, v180
	v_lshlrev_b32_e32 v152, 16, v181
	v_and_b32_e32 v153, 0xffff0000, v181
	v_pk_mul_f32 v[154:155], v[84:85], v[146:147]
	v_pk_mul_f32 v[156:157], v[86:87], v[148:149]
	v_pk_mul_f32 v[158:159], v[80:81], v[150:151]
	v_pk_mul_f32 v[160:161], v[82:83], v[152:153]
	v_cvt_pk_bf16_f32 v178, v154, v155
	v_cvt_pk_bf16_f32 v179, v156, v157
	v_cvt_pk_bf16_f32 v180, v158, v159
	v_cvt_pk_bf16_f32 v181, v160, v161
	global_store_dwordx4 v145, v[178:181], s[72:73] offset:256 nt
	s_waitcnt vmcnt(15)
	v_lshlrev_b32_e32 v146, 16, v184
	v_and_b32_e32 v147, 0xffff0000, v184
	v_lshlrev_b32_e32 v148, 16, v185
	v_and_b32_e32 v149, 0xffff0000, v185
	v_lshlrev_b32_e32 v150, 16, v186
	v_and_b32_e32 v151, 0xffff0000, v186
	v_lshlrev_b32_e32 v152, 16, v187
	v_and_b32_e32 v153, 0xffff0000, v187
	v_pk_mul_f32 v[154:155], v[108:109], v[146:147]
	v_pk_mul_f32 v[156:157], v[110:111], v[148:149]
	v_pk_mul_f32 v[158:159], v[104:105], v[150:151]
	v_pk_mul_f32 v[160:161], v[106:107], v[152:153]
	v_add_u32_e32 v144, 0x40000, v143
	v_cvt_pk_bf16_f32 v184, v154, v155
	v_cvt_pk_bf16_f32 v185, v156, v157
	v_cvt_pk_bf16_f32 v186, v158, v159
	v_cvt_pk_bf16_f32 v187, v160, v161
	global_store_dwordx4 v144, v[184:187], s[72:73] nt
	s_waitcnt vmcnt(15)
	v_lshlrev_b32_e32 v146, 16, v188
	v_and_b32_e32 v147, 0xffff0000, v188
	v_lshlrev_b32_e32 v148, 16, v189
	v_and_b32_e32 v149, 0xffff0000, v189
	v_lshlrev_b32_e32 v150, 16, v190
	v_and_b32_e32 v151, 0xffff0000, v190
	v_lshlrev_b32_e32 v152, 16, v191
	v_and_b32_e32 v153, 0xffff0000, v191
	v_pk_mul_f32 v[154:155], v[76:77], v[146:147]
	v_pk_mul_f32 v[156:157], v[78:79], v[148:149]
	v_pk_mul_f32 v[158:159], v[72:73], v[150:151]
	v_pk_mul_f32 v[160:161], v[74:75], v[152:153]
	v_cvt_pk_bf16_f32 v188, v154, v155
	v_cvt_pk_bf16_f32 v189, v156, v157
	v_cvt_pk_bf16_f32 v190, v158, v159
	v_cvt_pk_bf16_f32 v191, v160, v161
	global_store_dwordx4 v144, v[188:191], s[72:73] offset:256 nt
	s_waitcnt vmcnt(15)
	v_lshlrev_b32_e32 v146, 16, v192
	v_and_b32_e32 v147, 0xffff0000, v192
	v_lshlrev_b32_e32 v148, 16, v193
	v_and_b32_e32 v149, 0xffff0000, v193
	v_lshlrev_b32_e32 v150, 16, v194
	v_and_b32_e32 v151, 0xffff0000, v194
	v_lshlrev_b32_e32 v152, 16, v195
	v_and_b32_e32 v153, 0xffff0000, v195
	v_pk_mul_f32 v[154:155], v[100:101], v[146:147]
	v_pk_mul_f32 v[156:157], v[102:103], v[148:149]
	v_pk_mul_f32 v[158:159], v[96:97], v[150:151]
	v_pk_mul_f32 v[160:161], v[98:99], v[152:153]
	v_add_u32_e32 v145, 0x60000, v143
	v_cvt_pk_bf16_f32 v192, v154, v155
	v_cvt_pk_bf16_f32 v193, v156, v157
	v_cvt_pk_bf16_f32 v194, v158, v159
	v_cvt_pk_bf16_f32 v195, v160, v161
	global_store_dwordx4 v145, v[192:195], s[72:73] nt
	s_waitcnt vmcnt(15)
	v_lshlrev_b32_e32 v146, 16, v196
	v_and_b32_e32 v147, 0xffff0000, v196
	v_lshlrev_b32_e32 v148, 16, v197
	v_and_b32_e32 v149, 0xffff0000, v197
	v_lshlrev_b32_e32 v150, 16, v198
	v_and_b32_e32 v151, 0xffff0000, v198
	v_lshlrev_b32_e32 v152, 16, v199
	v_and_b32_e32 v153, 0xffff0000, v199
	v_pk_mul_f32 v[154:155], v[68:69], v[146:147]
	v_pk_mul_f32 v[156:157], v[70:71], v[148:149]
	v_pk_mul_f32 v[158:159], v[64:65], v[150:151]
	v_pk_mul_f32 v[160:161], v[66:67], v[152:153]
	v_cvt_pk_bf16_f32 v196, v154, v155
	v_cvt_pk_bf16_f32 v197, v156, v157
	v_cvt_pk_bf16_f32 v198, v158, v159
	v_cvt_pk_bf16_f32 v199, v160, v161
	global_store_dwordx4 v145, v[196:199], s[72:73] offset:256 nt
	s_waitcnt vmcnt(15)
	v_lshlrev_b32_e32 v146, 16, v200
	v_and_b32_e32 v147, 0xffff0000, v200
	v_lshlrev_b32_e32 v148, 16, v201
	v_and_b32_e32 v149, 0xffff0000, v201
	v_lshlrev_b32_e32 v150, 16, v202
	v_and_b32_e32 v151, 0xffff0000, v202
	v_lshlrev_b32_e32 v152, 16, v203
	v_and_b32_e32 v153, 0xffff0000, v203
	v_pk_mul_f32 v[154:155], v[60:61], v[146:147]
	v_pk_mul_f32 v[156:157], v[62:63], v[148:149]
	v_pk_mul_f32 v[158:159], v[56:57], v[150:151]
	v_pk_mul_f32 v[160:161], v[58:59], v[152:153]
	v_add_u32_e32 v144, 0x100000, v143
	v_cvt_pk_bf16_f32 v200, v154, v155
	v_cvt_pk_bf16_f32 v201, v156, v157
	v_cvt_pk_bf16_f32 v202, v158, v159
	v_cvt_pk_bf16_f32 v203, v160, v161
	global_store_dwordx4 v144, v[200:203], s[72:73] nt
	s_waitcnt vmcnt(15)
	v_lshlrev_b32_e32 v146, 16, v204
	v_and_b32_e32 v147, 0xffff0000, v204
	v_lshlrev_b32_e32 v148, 16, v205
	v_and_b32_e32 v149, 0xffff0000, v205
	v_lshlrev_b32_e32 v150, 16, v206
	v_and_b32_e32 v151, 0xffff0000, v206
	v_lshlrev_b32_e32 v152, 16, v207
	v_and_b32_e32 v153, 0xffff0000, v207
	v_pk_mul_f32 v[154:155], v[28:29], v[146:147]
	v_pk_mul_f32 v[156:157], v[30:31], v[148:149]
	v_pk_mul_f32 v[158:159], v[24:25], v[150:151]
	v_pk_mul_f32 v[160:161], v[26:27], v[152:153]
	v_cvt_pk_bf16_f32 v204, v154, v155
	v_cvt_pk_bf16_f32 v205, v156, v157
	v_cvt_pk_bf16_f32 v206, v158, v159
	v_cvt_pk_bf16_f32 v207, v160, v161
	global_store_dwordx4 v144, v[204:207], s[72:73] offset:256 nt
	s_waitcnt vmcnt(15)
	v_lshlrev_b32_e32 v146, 16, v208
	v_and_b32_e32 v147, 0xffff0000, v208
	v_lshlrev_b32_e32 v148, 16, v209
	v_and_b32_e32 v149, 0xffff0000, v209
	v_lshlrev_b32_e32 v150, 16, v210
	v_and_b32_e32 v151, 0xffff0000, v210
	v_lshlrev_b32_e32 v152, 16, v211
	v_and_b32_e32 v153, 0xffff0000, v211
	v_pk_mul_f32 v[154:155], v[52:53], v[146:147]
	v_pk_mul_f32 v[156:157], v[54:55], v[148:149]
	v_pk_mul_f32 v[158:159], v[48:49], v[150:151]
	v_pk_mul_f32 v[160:161], v[50:51], v[152:153]
	v_add_u32_e32 v145, 0x120000, v143
	v_cvt_pk_bf16_f32 v208, v154, v155
	v_cvt_pk_bf16_f32 v209, v156, v157
	v_cvt_pk_bf16_f32 v210, v158, v159
	v_cvt_pk_bf16_f32 v211, v160, v161
	global_store_dwordx4 v145, v[208:211], s[72:73] nt
	s_waitcnt vmcnt(15)
	v_lshlrev_b32_e32 v146, 16, v212
	v_and_b32_e32 v147, 0xffff0000, v212
	v_lshlrev_b32_e32 v148, 16, v213
	v_and_b32_e32 v149, 0xffff0000, v213
	v_lshlrev_b32_e32 v150, 16, v214
	v_and_b32_e32 v151, 0xffff0000, v214
	v_lshlrev_b32_e32 v152, 16, v215
	v_and_b32_e32 v153, 0xffff0000, v215
	v_pk_mul_f32 v[154:155], v[20:21], v[146:147]
	v_pk_mul_f32 v[156:157], v[22:23], v[148:149]
	v_pk_mul_f32 v[158:159], v[16:17], v[150:151]
	v_pk_mul_f32 v[160:161], v[18:19], v[152:153]
	v_cvt_pk_bf16_f32 v212, v154, v155
	v_cvt_pk_bf16_f32 v213, v156, v157
	v_cvt_pk_bf16_f32 v214, v158, v159
	v_cvt_pk_bf16_f32 v215, v160, v161
	global_store_dwordx4 v145, v[212:215], s[72:73] offset:256 nt
	s_waitcnt vmcnt(15)
	v_lshlrev_b32_e32 v146, 16, v216
	v_and_b32_e32 v147, 0xffff0000, v216
	v_lshlrev_b32_e32 v148, 16, v217
	v_and_b32_e32 v149, 0xffff0000, v217
	v_lshlrev_b32_e32 v150, 16, v218
	v_and_b32_e32 v151, 0xffff0000, v218
	v_lshlrev_b32_e32 v152, 16, v219
	v_and_b32_e32 v153, 0xffff0000, v219
	v_pk_mul_f32 v[154:155], v[44:45], v[146:147]
	v_pk_mul_f32 v[156:157], v[46:47], v[148:149]
	v_pk_mul_f32 v[158:159], v[40:41], v[150:151]
	v_pk_mul_f32 v[160:161], v[42:43], v[152:153]
	v_add_u32_e32 v144, 0x140000, v143
	v_cvt_pk_bf16_f32 v216, v154, v155
	v_cvt_pk_bf16_f32 v217, v156, v157
	v_cvt_pk_bf16_f32 v218, v158, v159
	v_cvt_pk_bf16_f32 v219, v160, v161
	global_store_dwordx4 v144, v[216:219], s[72:73] nt
	s_waitcnt vmcnt(15)
	v_lshlrev_b32_e32 v146, 16, v220
	v_and_b32_e32 v147, 0xffff0000, v220
	v_lshlrev_b32_e32 v148, 16, v221
	v_and_b32_e32 v149, 0xffff0000, v221
	v_lshlrev_b32_e32 v150, 16, v222
	v_and_b32_e32 v151, 0xffff0000, v222
	v_lshlrev_b32_e32 v152, 16, v223
	v_and_b32_e32 v153, 0xffff0000, v223
	v_pk_mul_f32 v[154:155], v[12:13], v[146:147]
	v_pk_mul_f32 v[156:157], v[14:15], v[148:149]
	v_pk_mul_f32 v[158:159], v[8:9], v[150:151]
	v_pk_mul_f32 v[160:161], v[10:11], v[152:153]
	v_cvt_pk_bf16_f32 v220, v154, v155
	v_cvt_pk_bf16_f32 v221, v156, v157
	v_cvt_pk_bf16_f32 v222, v158, v159
	v_cvt_pk_bf16_f32 v223, v160, v161
	global_store_dwordx4 v144, v[220:223], s[72:73] offset:256 nt
	s_waitcnt vmcnt(15)
	v_lshlrev_b32_e32 v146, 16, v224
	v_and_b32_e32 v147, 0xffff0000, v224
	v_lshlrev_b32_e32 v148, 16, v225
	v_and_b32_e32 v149, 0xffff0000, v225
	v_lshlrev_b32_e32 v150, 16, v226
	v_and_b32_e32 v151, 0xffff0000, v226
	v_lshlrev_b32_e32 v152, 16, v227
	v_and_b32_e32 v153, 0xffff0000, v227
	v_pk_mul_f32 v[154:155], v[36:37], v[146:147]
	v_pk_mul_f32 v[156:157], v[38:39], v[148:149]
	v_pk_mul_f32 v[158:159], v[32:33], v[150:151]
	v_pk_mul_f32 v[160:161], v[34:35], v[152:153]
	v_add_u32_e32 v145, 0x160000, v143
	v_cvt_pk_bf16_f32 v224, v154, v155
	v_cvt_pk_bf16_f32 v225, v156, v157
	v_cvt_pk_bf16_f32 v226, v158, v159
	v_cvt_pk_bf16_f32 v227, v160, v161
	global_store_dwordx4 v145, v[224:227], s[72:73] nt
	s_waitcnt vmcnt(15)
	v_lshlrev_b32_e32 v146, 16, v228
	v_and_b32_e32 v147, 0xffff0000, v228
	v_lshlrev_b32_e32 v148, 16, v229
	v_and_b32_e32 v149, 0xffff0000, v229
	v_lshlrev_b32_e32 v150, 16, v230
	v_and_b32_e32 v151, 0xffff0000, v230
	v_lshlrev_b32_e32 v152, 16, v231
	v_and_b32_e32 v153, 0xffff0000, v231
	v_pk_mul_f32 v[154:155], v[4:5], v[146:147]
	v_pk_mul_f32 v[156:157], v[6:7], v[148:149]
	v_pk_mul_f32 v[158:159], v[0:1], v[150:151]
	v_pk_mul_f32 v[160:161], v[2:3], v[152:153]
	v_cvt_pk_bf16_f32 v228, v154, v155
	v_cvt_pk_bf16_f32 v229, v156, v157
	v_cvt_pk_bf16_f32 v230, v158, v159
	v_cvt_pk_bf16_f32 v231, v160, v161
	global_store_dwordx4 v145, v[228:231], s[72:73] offset:256 nt

.LBB0_486:
	v_lshl_add_u32 v148, s20, 8, v142
	v_lshl_or_b32 v150, s21, 8, v144
	v_ashrrev_i32_e32 v149, 31, v148
	v_ashrrev_i32_e32 v151, 31, v150
	v_lshlrev_b64 v[152:153], 13, v[148:149]
	v_lshl_add_u64 v[152:153], s[92:93], 0, v[152:153]
	v_lshlrev_b64 v[150:151], 1, v[150:151]
	v_lshl_add_u64 v[152:153], v[152:153], 0, v[150:151]
	v_cvt_pk_bf16_f32 v60, v60, v61
	v_cvt_pk_bf16_f32 v61, v62, v63
	v_cvt_pk_bf16_f32 v62, v56, v57
	v_add_co_u32_e32 v56, vcc, s55, v152
	v_cvt_pk_bf16_f32 v68, v68, v69
	v_cvt_pk_bf16_f32 v69, v70, v71
	v_cvt_pk_bf16_f32 v70, v64, v65
	v_lshl_add_u64 v[64:65], v[152:153], 0, s[6:7]
	v_addc_co_u32_e32 v57, vcc, 0, v153, vcc
	v_cvt_pk_bf16_f32 v44, v44, v45
	v_cvt_pk_bf16_f32 v45, v46, v47
	v_cvt_pk_bf16_f32 v46, v40, v41
	v_cvt_pk_bf16_f32 v47, v42, v43
	v_cvt_pk_bf16_f32 v108, v108, v109
	v_cvt_pk_bf16_f32 v109, v110, v111
	v_cvt_pk_bf16_f32 v110, v104, v105
	v_or_b32_e32 v104, 16, v148
	global_store_dwordx4 v[64:65], v[44:47], off offset:256 nt
	v_ashrrev_i32_e32 v105, 31, v104
	v_cvt_pk_bf16_f32 v92, v92, v93
	v_add_co_u32_e32 v46, vcc, s56, v152
	v_cvt_pk_bf16_f32 v93, v94, v95
	v_cvt_pk_bf16_f32 v94, v88, v89
	v_or_b32_e32 v88, 32, v148
	v_lshl_add_u64 v[44:45], v[152:153], 0, s[14:15]
	v_addc_co_u32_e32 v47, vcc, 0, v153, vcc
	v_cvt_pk_bf16_f32 v28, v28, v29
	v_cvt_pk_bf16_f32 v29, v30, v31
	v_cvt_pk_bf16_f32 v30, v24, v25
	v_cvt_pk_bf16_f32 v31, v26, v27
	v_lshlrev_b64 v[104:105], 13, v[104:105]
	v_ashrrev_i32_e32 v89, 31, v88
	v_cvt_pk_bf16_f32 v76, v76, v77
	v_cvt_pk_bf16_f32 v77, v78, v79
	v_cvt_pk_bf16_f32 v78, v72, v73
	v_or_b32_e32 v72, 48, v148
	global_store_dwordx4 v[44:45], v[28:31], off offset:256 nt
	v_cvt_pk_bf16_f32 v111, v106, v107
	v_lshl_add_u64 v[104:105], s[92:93], 0, v[104:105]
	v_add_co_u32_e32 v30, vcc, s57, v152
	v_lshlrev_b64 v[88:89], 13, v[88:89]
	v_ashrrev_i32_e32 v73, 31, v72
	v_lshl_add_u64 v[28:29], v[152:153], 0, s[16:17]
	v_addc_co_u32_e32 v31, vcc, 0, v153, vcc
	v_cvt_pk_bf16_f32 v12, v12, v13
	v_cvt_pk_bf16_f32 v13, v14, v15
	v_cvt_pk_bf16_f32 v14, v8, v9
	v_cvt_pk_bf16_f32 v15, v10, v11
	global_store_dwordx4 v[152:153], v[108:111], off offset:256 nt
	v_cvt_pk_bf16_f32 v95, v90, v91
	v_lshl_add_u64 v[88:89], s[92:93], 0, v[88:89]
	v_lshl_add_u64 v[108:109], v[104:105], 0, v[150:151]
	v_lshlrev_b64 v[72:73], 13, v[72:73]
	global_store_dwordx4 v[28:29], v[12:15], off offset:256 nt
	global_store_dwordx4 v[108:109], v[92:95], off offset:256 nt
	v_cvt_pk_bf16_f32 v79, v74, v75
	v_add_co_u32_e32 v14, vcc, s58, v152
	v_lshl_add_u64 v[92:93], v[88:89], 0, v[150:151]
	v_lshl_add_u64 v[72:73], s[92:93], 0, v[72:73]
	v_addc_co_u32_e32 v15, vcc, 0, v153, vcc
	v_cvt_pk_bf16_f32 v124, v124, v125
	v_cvt_pk_bf16_f32 v125, v126, v127
	v_cvt_pk_bf16_f32 v126, v120, v121
	v_cvt_pk_bf16_f32 v127, v122, v123
	v_cvt_pk_bf16_f32 v104, v116, v117
	v_cvt_pk_bf16_f32 v105, v118, v119
	v_cvt_pk_bf16_f32 v106, v112, v113
	v_cvt_pk_bf16_f32 v107, v114, v115
	v_cvt_pk_bf16_f32 v88, v100, v101
	v_cvt_pk_bf16_f32 v89, v102, v103
	v_cvt_pk_bf16_f32 v90, v96, v97
	v_cvt_pk_bf16_f32 v91, v98, v99
	global_store_dwordx4 v[92:93], v[76:79], off offset:256 nt
	v_cvt_pk_bf16_f32 v74, v80, v81
	v_cvt_pk_bf16_f32 v75, v82, v83
	v_lshl_add_u64 v[76:77], v[72:73], 0, v[150:151]
	v_cvt_pk_bf16_f32 v72, v84, v85
	v_cvt_pk_bf16_f32 v73, v86, v87
	v_cvt_pk_bf16_f32 v71, v66, v67
	v_cvt_pk_bf16_f32 v63, v58, v59
	v_cvt_pk_bf16_f32 v40, v52, v53
	v_cvt_pk_bf16_f32 v41, v54, v55
	v_cvt_pk_bf16_f32 v42, v48, v49
	v_cvt_pk_bf16_f32 v43, v50, v51
	v_cvt_pk_bf16_f32 v24, v36, v37
	v_cvt_pk_bf16_f32 v25, v38, v39
	v_cvt_pk_bf16_f32 v26, v32, v33
	v_cvt_pk_bf16_f32 v27, v34, v35
	v_lshl_add_u64 v[12:13], v[152:153], 0, s[18:19]
	v_cvt_pk_bf16_f32 v8, v20, v21
	v_cvt_pk_bf16_f32 v9, v22, v23
	v_cvt_pk_bf16_f32 v10, v16, v17
	v_cvt_pk_bf16_f32 v11, v18, v19
	v_cvt_pk_bf16_f32 v4, v4, v5
	v_cvt_pk_bf16_f32 v5, v6, v7
	v_cvt_pk_bf16_f32 v6, v0, v1
	v_cvt_pk_bf16_f32 v7, v2, v3
	s_andn2_b64 vcc, exec, s[26:27]
	s_mov_b64 s[20:21], -1
	global_store_dwordx4 v[152:153], v[124:127], off nt
	global_store_dwordx4 v[108:109], v[104:107], off nt
	global_store_dwordx4 v[92:93], v[88:91], off nt
	global_store_dwordx4 v[76:77], v[72:75], off nt
	global_store_dwordx4 v[76:77], v[68:71], off offset:256 nt
	global_store_dwordx4 v[56:57], v[60:63], off nt
	global_store_dwordx4 v[46:47], v[40:43], off nt
	global_store_dwordx4 v[30:31], v[24:27], off nt
	global_store_dwordx4 v[14:15], v[8:11], off nt
	global_store_dwordx4 v[12:13], v[4:7], off offset:256 nt
	s_cbranch_vccnz .LBB0_474
	s_andn2_b64 vcc, exec, s[8:9]
	s_cbranch_vccnz .LBB0_473
	s_barrier
	s_branch .LBB0_473
